# sample-attn loop: rsqrt chain spread through the score MFMAs LDS waits; rope-sum reads of the next tile issued behind barrier 2
# speedup vs baseline: 1.0092x; 1.0043x over previous
.LBB0_1607:
	s_or_b64 exec, exec, s[2:3]
	v_mov_b32_e32 v187, 0
	v_mov_b32_e32 v186, v187
	v_mov_b32_e32 v189, v187
	v_mov_b32_e32 v188, v187
	v_mov_b32_e32 v15, v187
	v_mov_b32_e32 v14, v187
	v_mov_b32_e32 v13, v187
	v_mov_b32_e32 v12, v187
	v_mov_b32_e32 v11, v187
	v_mov_b32_e32 v10, v187
	v_mov_b32_e32 v9, v187
	v_mov_b32_e32 v8, v187
	v_mov_b32_e32 v7, v187
	v_mov_b32_e32 v6, v187
	v_mov_b32_e32 v5, v187
	v_mov_b32_e32 v4, v187
	v_mov_b32_e32 v3, v187
	v_mov_b32_e32 v2, v187
	v_mov_b32_e32 v1, v187
	v_mov_b32_e32 v0, v187
	s_waitcnt lgkmcnt(0)
	s_barrier
	s_cmp_lg_u32 s42, 0
	s_cbranch_scc1 .LBB0_1608
	ds_read_b128 v[246:249], v207
	ds_read_b128 v[250:253], v207 offset:16
	ds_read_b128 v[24:27], v207 offset:64
	ds_read_b128 v[28:31], v207 offset:80
	s_waitcnt lgkmcnt(2)
	v_mfma_scale_f32_32x32x64_f8f6f4 v[230:245], v[32:39], v[246:253], 0, v208, v208 op_sel_hi:[0,0,0]
	ds_read_b128 v[246:249], v207 offset:128
	ds_read_b128 v[250:253], v207 offset:144
	s_waitcnt lgkmcnt(2)
	v_mfma_scale_f32_32x32x64_f8f6f4 v[230:245], v[40:47], v[24:31], v[230:245], v208, v208 op_sel_hi:[0,0,0]
	ds_read_b128 v[24:27], v207 offset:192
	ds_read_b128 v[28:31], v207 offset:208
	s_waitcnt lgkmcnt(2)
	v_mfma_scale_f32_32x32x64_f8f6f4 v[230:245], v[48:55], v[246:253], v[230:245], v208, v208 op_sel_hi:[0,0,0]
	ds_read_b128 v[246:249], v207
	ds_read_b128 v[250:253], v207 offset:16
	s_waitcnt lgkmcnt(2)
	v_mfma_scale_f32_32x32x64_f8f6f4 v[230:245], v[56:63], v[24:31], v[230:245], v208, v208 op_sel_hi:[0,0,0]
	ds_read_b128 v[24:27], v207 offset:64
	ds_read_b128 v[28:31], v207 offset:80
	s_nop 15
	s_nop 1
	v_mul_f32_e32 v180, v231, v231
	v_fmac_f32_e32 v180, v230, v230
	v_fmac_f32_e32 v180, v232, v232
	v_fmac_f32_e32 v180, v233, v233
	v_fmac_f32_e32 v180, v234, v234
	v_fmac_f32_e32 v180, v235, v235
	v_fmac_f32_e32 v180, v236, v236
	v_fmac_f32_e32 v180, v237, v237
	v_fmac_f32_e32 v180, v238, v238
	v_fmac_f32_e32 v180, v239, v239
	v_fmac_f32_e32 v180, v240, v240
	v_fmac_f32_e32 v180, v241, v241
	v_fmac_f32_e32 v180, v242, v242
	v_fmac_f32_e32 v180, v243, v243
	v_fmac_f32_e32 v180, v244, v244
	v_fmac_f32_e32 v180, v245, v245
	s_waitcnt lgkmcnt(2)
	v_mfma_scale_f32_32x32x64_f8f6f4 v[230:245], v[64:71], v[246:253], 0, v208, v208 op_sel_hi:[0,0,0]
	ds_read_b128 v[246:249], v207 offset:128
	ds_read_b128 v[250:253], v207 offset:144
	s_waitcnt lgkmcnt(2)
	v_mfma_scale_f32_32x32x64_f8f6f4 v[230:245], v[72:79], v[24:31], v[230:245], v208, v208 op_sel_hi:[0,0,0]
	ds_read_b128 v[24:27], v207 offset:192
	ds_read_b128 v[28:31], v207 offset:208
	s_waitcnt lgkmcnt(2)
	v_mfma_scale_f32_32x32x64_f8f6f4 v[230:245], v[80:87], v[246:253], v[230:245], v208, v208 op_sel_hi:[0,0,0]
	ds_read_b128 v[246:249], v207 offset:8704
	ds_read_b128 v[250:253], v207 offset:8720
	s_waitcnt lgkmcnt(2)
	v_mfma_scale_f32_32x32x64_f8f6f4 v[230:245], v[88:95], v[24:31], v[230:245], v208, v208 op_sel_hi:[0,0,0]
	ds_read_b128 v[24:27], v207 offset:8768
	ds_read_b128 v[28:31], v207 offset:8784
	s_nop 15
	s_nop 1
	v_fmac_f32_e32 v180, v230, v230
	v_fmac_f32_e32 v180, v231, v231
	v_fmac_f32_e32 v180, v232, v232
	v_fmac_f32_e32 v180, v233, v233
	v_fmac_f32_e32 v180, v234, v234
	v_fmac_f32_e32 v180, v235, v235
	v_fmac_f32_e32 v180, v236, v236
	v_fmac_f32_e32 v180, v237, v237
	v_fmac_f32_e32 v180, v238, v238
	v_fmac_f32_e32 v180, v239, v239
	v_fmac_f32_e32 v180, v240, v240
	v_fmac_f32_e32 v180, v241, v241
	v_fmac_f32_e32 v180, v242, v242
	v_fmac_f32_e32 v180, v243, v243
	v_fmac_f32_e32 v180, v244, v244
	v_fmac_f32_e32 v180, v245, v245
	s_waitcnt lgkmcnt(2)
	v_mfma_scale_f32_32x32x64_f8f6f4 v[230:245], v[32:39], v[246:253], 0, v208, v208 op_sel_hi:[0,0,0]
	ds_read_b128 v[246:249], v207 offset:8832
	ds_read_b128 v[250:253], v207 offset:8848
	s_waitcnt lgkmcnt(2)
	v_mfma_scale_f32_32x32x64_f8f6f4 v[230:245], v[40:47], v[24:31], v[230:245], v208, v208 op_sel_hi:[0,0,0]
	ds_read_b128 v[24:27], v207 offset:8896
	ds_read_b128 v[28:31], v207 offset:8912
	s_waitcnt lgkmcnt(2)
	v_mfma_scale_f32_32x32x64_f8f6f4 v[230:245], v[48:55], v[246:253], v[230:245], v208, v208 op_sel_hi:[0,0,0]
	ds_read_b128 v[246:249], v207 offset:8704
	ds_read_b128 v[250:253], v207 offset:8720
	s_waitcnt lgkmcnt(2)
	v_mfma_scale_f32_32x32x64_f8f6f4 v[230:245], v[56:63], v[24:31], v[230:245], v208, v208 op_sel_hi:[0,0,0]
	ds_read_b128 v[24:27], v207 offset:8768
	ds_read_b128 v[28:31], v207 offset:8784
	s_nop 15
	s_nop 1
	v_mul_f32_e32 v229, v231, v231
	v_fmac_f32_e32 v229, v230, v230
	v_fmac_f32_e32 v229, v232, v232
	v_fmac_f32_e32 v229, v233, v233
	v_fmac_f32_e32 v229, v234, v234
	v_fmac_f32_e32 v229, v235, v235
	v_fmac_f32_e32 v229, v236, v236
	v_fmac_f32_e32 v229, v237, v237
	v_fmac_f32_e32 v229, v238, v238
	v_fmac_f32_e32 v229, v239, v239
	v_fmac_f32_e32 v229, v240, v240
	v_fmac_f32_e32 v229, v241, v241
	v_fmac_f32_e32 v229, v242, v242
	v_fmac_f32_e32 v229, v243, v243
	v_fmac_f32_e32 v229, v244, v244
	v_fmac_f32_e32 v229, v245, v245
	s_waitcnt lgkmcnt(2)
	v_mfma_scale_f32_32x32x64_f8f6f4 v[230:245], v[64:71], v[246:253], 0, v208, v208 op_sel_hi:[0,0,0]
	ds_read_b128 v[246:249], v207 offset:8832
	ds_read_b128 v[250:253], v207 offset:8848
	s_waitcnt lgkmcnt(2)
	v_mfma_scale_f32_32x32x64_f8f6f4 v[230:245], v[72:79], v[24:31], v[230:245], v208, v208 op_sel_hi:[0,0,0]
	ds_read_b128 v[24:27], v207 offset:8896
	ds_read_b128 v[28:31], v207 offset:8912
	s_waitcnt lgkmcnt(2)
	v_mfma_scale_f32_32x32x64_f8f6f4 v[230:245], v[80:87], v[246:253], v[230:245], v208, v208 op_sel_hi:[0,0,0]
	s_waitcnt lgkmcnt(0)
	v_mfma_scale_f32_32x32x64_f8f6f4 v[230:245], v[88:95], v[24:31], v[230:245], v208, v208 op_sel_hi:[0,0,0]
	s_nop 15
	s_nop 3
	v_fmac_f32_e32 v229, v230, v230
	v_fmac_f32_e32 v229, v231, v231
	v_fmac_f32_e32 v229, v232, v232
	v_fmac_f32_e32 v229, v233, v233
	v_fmac_f32_e32 v229, v234, v234
	v_fmac_f32_e32 v229, v235, v235
	v_fmac_f32_e32 v229, v236, v236
	v_fmac_f32_e32 v229, v237, v237
	v_fmac_f32_e32 v229, v238, v238
	v_fmac_f32_e32 v229, v239, v239
	v_fmac_f32_e32 v229, v240, v240
	v_fmac_f32_e32 v229, v241, v241
	v_fmac_f32_e32 v229, v242, v242
	v_fmac_f32_e32 v229, v243, v243
	v_fmac_f32_e32 v229, v244, v244
	v_fmac_f32_e32 v229, v245, v245
	ds_read_b128 v[238:241], v214 offset:512
	ds_read_b128 v[242:245], v214 offset:528
	ds_read_b128 v[246:249], v214 offset:19456
	ds_read_b128 v[250:253], v214 offset:19472
.LBB0_1608:
	s_waitcnt lgkmcnt(0)
	v_lshlrev_b32_e32 v24, 16, v238
	v_and_b32_e32 v238, 0xffff0000, v238
	v_mul_f32_e32 v28, v238, v238
	v_fmac_f32_e32 v28, v24, v24
	v_lshlrev_b32_e32 v25, 16, v239
	v_and_b32_e32 v239, 0xffff0000, v239
	v_fmac_f32_e32 v28, v25, v25
	v_fmac_f32_e32 v28, v239, v239
	v_lshlrev_b32_e32 v26, 16, v240
	v_and_b32_e32 v240, 0xffff0000, v240
	v_fmac_f32_e32 v28, v26, v26
	v_fmac_f32_e32 v28, v240, v240
	v_lshlrev_b32_e32 v27, 16, v241
	v_and_b32_e32 v241, 0xffff0000, v241
	v_fmac_f32_e32 v28, v27, v27
	v_fmac_f32_e32 v28, v241, v241
	v_lshlrev_b32_e32 v24, 16, v242
	v_and_b32_e32 v242, 0xffff0000, v242
	v_fmac_f32_e32 v28, v24, v24
	v_fmac_f32_e32 v28, v242, v242
	v_lshlrev_b32_e32 v25, 16, v243
	v_and_b32_e32 v243, 0xffff0000, v243
	v_fmac_f32_e32 v28, v25, v25
	v_fmac_f32_e32 v28, v243, v243
	v_lshlrev_b32_e32 v26, 16, v244
	v_and_b32_e32 v244, 0xffff0000, v244
	v_fmac_f32_e32 v28, v26, v26
	v_fmac_f32_e32 v28, v244, v244
	v_lshlrev_b32_e32 v27, 16, v245
	v_and_b32_e32 v245, 0xffff0000, v245
	v_fmac_f32_e32 v28, v27, v27
	v_fmac_f32_e32 v28, v245, v245
	v_lshlrev_b32_e32 v24, 16, v246
	v_and_b32_e32 v246, 0xffff0000, v246
	v_mul_f32_e32 v29, v246, v246
	v_fmac_f32_e32 v29, v24, v24
	v_lshlrev_b32_e32 v25, 16, v247
	v_and_b32_e32 v247, 0xffff0000, v247
	v_fmac_f32_e32 v29, v25, v25
	v_fmac_f32_e32 v29, v247, v247
	v_lshlrev_b32_e32 v26, 16, v248
	v_and_b32_e32 v248, 0xffff0000, v248
	v_fmac_f32_e32 v29, v26, v26
	v_fmac_f32_e32 v29, v248, v248
	v_lshlrev_b32_e32 v27, 16, v249
	v_and_b32_e32 v249, 0xffff0000, v249
	v_fmac_f32_e32 v29, v27, v27
	v_fmac_f32_e32 v29, v249, v249
	v_lshlrev_b32_e32 v24, 16, v250
	v_and_b32_e32 v250, 0xffff0000, v250
	v_fmac_f32_e32 v29, v24, v24
	v_fmac_f32_e32 v29, v250, v250
	v_lshlrev_b32_e32 v25, 16, v251
	v_and_b32_e32 v251, 0xffff0000, v251
	v_fmac_f32_e32 v29, v25, v25
	v_fmac_f32_e32 v29, v251, v251
	v_lshlrev_b32_e32 v26, 16, v252
	v_and_b32_e32 v252, 0xffff0000, v252
	v_fmac_f32_e32 v29, v26, v26
	v_fmac_f32_e32 v29, v252, v252
	v_lshlrev_b32_e32 v27, 16, v253
	v_and_b32_e32 v253, 0xffff0000, v253
	v_fmac_f32_e32 v29, v27, v27
	v_fmac_f32_e32 v29, v253, v253
	v_fmac_f32_e32 v28, 0x3b800000, v180
	v_fmac_f32_e32 v29, 0x3b800000, v229
	v_mov_b32_e32 v250, v28
	v_mov_b32_e32 v251, v29
	ds_bpermute_b32 v249, v199, v250
	ds_bpermute_b32 v248, v199, v251
.LBB0_1610:
	s_nop 0
	ds_read_b128 v[16:19], v215
	ds_read_b128 v[20:23], v216
	ds_read_b128 v[24:27], v215 offset:64
	ds_read_b128 v[28:31], v216 offset:64
	ds_read_b128 v[190:193], v215 offset:512
	s_add_i32 s43, s42, 1
	s_waitcnt lgkmcnt(5)
	v_add_f32_e32 v246, v250, v249
	v_add_f32_e32 v247, v251, v248
	v_cndmask_b32_e64 v246, v247, v246, s[6:7]
	v_fmamk_f32 v246, v246, 0x3c2aaaab, v209
	v_mul_f32_e32 v249, 0x4f800000, v246
	v_cmp_gt_f32_e32 vcc, s37, v246
	s_waitcnt lgkmcnt(3)
	v_mfma_f32_16x16x32_bf16 v[16:19], v[16:19], v[20:23], 0
	ds_read_b128 v[20:23], v215 offset:128
	ds_read_b128 v[230:233], v216 offset:128
	s_cmp_ge_u32 s43, s39
	s_nop 1
	v_cndmask_b32_e32 v246, v246, v249, vcc
	v_sqrt_f32_e32 v249, v246
	s_nop 0
	v_add_u32_e32 v250, -1, v249
	v_fma_f32 v252, -v250, v249, v246
	v_add_u32_e32 v251, 1, v249
	s_waitcnt lgkmcnt(3)
	v_mfma_f32_16x16x32_bf16 v[16:19], v[24:27], v[28:31], v[16:19]
	ds_read_b128 v[24:27], v215 offset:192
	ds_read_b128 v[28:31], v216 offset:192
	v_cmp_ge_f32_e64 s[10:11], 0, v252
	s_nop 1
	v_cndmask_b32_e64 v250, v249, v250, s[10:11]
	v_fma_f32 v249, -v251, v249, v246
	v_cmp_lt_f32_e64 s[10:11], 0, v249
	s_nop 1
	v_cndmask_b32_e64 v249, v250, v251, s[10:11]
	s_waitcnt lgkmcnt(2)
	v_mfma_f32_16x16x32_bf16 v[16:19], v[20:23], v[230:233], v[16:19]
	ds_read_b128 v[20:23], v215 offset:256
	ds_read_b128 v[230:233], v216 offset:256
	v_mul_f32_e32 v250, 0x37800000, v249
	v_cndmask_b32_e32 v249, v249, v250, vcc
	v_cmp_class_f32_e32 vcc, v246, v210
	s_nop 1
	v_cndmask_b32_e32 v246, v249, v246, vcc
	v_div_scale_f32 v249, s[10:11], v246, v246, 1.0
	v_rcp_f32_e32 v250, v249
	s_waitcnt lgkmcnt(2)
	v_mfma_f32_16x16x32_bf16 v[16:19], v[24:27], v[28:31], v[16:19]
	ds_read_b128 v[24:27], v215 offset:320
	ds_read_b128 v[28:31], v216 offset:320
	s_nop 0
	v_fma_f32 v248, -v249, v250, 1.0
	v_fmac_f32_e32 v250, v248, v250
	v_div_scale_f32 v248, vcc, 1.0, v246, 1.0
	v_mul_f32_e32 v251, v248, v250
	v_fma_f32 v253, -v249, v251, v248
	v_fmac_f32_e32 v251, v253, v250
	s_waitcnt lgkmcnt(2)
	v_mfma_f32_16x16x32_bf16 v[16:19], v[20:23], v[230:233], v[16:19]
	ds_read_b128 v[20:23], v215 offset:384
	ds_read_b128 v[230:233], v216 offset:384
	v_fma_f32 v248, -v249, v251, v248
	s_nop 0
	v_div_fmas_f32 v248, v248, v250, v251
	v_div_fixup_f32 v246, v248, v246, 1.0
	s_waitcnt lgkmcnt(2)
	v_mfma_f32_16x16x32_bf16 v[16:19], v[24:27], v[28:31], v[16:19]
	ds_read_b128 v[24:27], v215 offset:448
	ds_read_b128 v[28:31], v216 offset:448
	ds_read_b128 v[234:237], v216 offset:512
	ds_write_b32 v203, v246
	s_waitcnt lgkmcnt(0)
	s_barrier
	v_mfma_f32_16x16x32_bf16 v[16:19], v[20:23], v[230:233], v[16:19]
	ds_read_b32 v20, v217
	v_mfma_f32_16x16x32_bf16 v[16:19], v[24:27], v[28:31], v[16:19]
	v_mfma_f32_16x16x32_bf16 v[16:19], v[190:193], v[234:237], v[16:19]
	ds_read_b128 v[246:249], v211
	ds_read_b128 v[250:253], v211 offset:16
	ds_read_b128 v[24:27], v211 offset:64
	ds_read_b128 v[28:31], v211 offset:80
	s_waitcnt lgkmcnt(4)
	s_nop 6
	v_fma_f32 v16, v16, v20, -v177
	v_fma_f32 v17, v17, v20, -v177
	v_fma_f32 v18, v18, v20, -v177
	v_fma_f32 v19, v19, v20, -v177
	v_exp_f32_e32 v192, v16
	v_exp_f32_e32 v193, v17
	v_exp_f32_e32 v190, v18
	v_exp_f32_e32 v191, v19
	v_bfe_u32 v16, v192, 16, 1
	v_bfe_u32 v17, v193, 16, 1
	v_bfe_u32 v18, v190, 16, 1
	v_bfe_u32 v19, v191, 16, 1
	v_add3_u32 v16, v192, v16, s38
	v_add3_u32 v17, v193, v17, s38
	v_add3_u32 v18, v190, v18, s38
	v_add3_u32 v19, v191, v19, s38
	ds_write_b16_d16_hi v218, v16
	ds_write_b16_d16_hi v218, v17 offset:144
	ds_write_b16_d16_hi v218, v18 offset:288
	ds_write_b16_d16_hi v218, v19 offset:432
	s_cbranch_scc1 .LBB0_1613
	s_waitcnt lgkmcnt(6)
	v_mfma_scale_f32_32x32x64_f8f6f4 v[230:245], v[32:39], v[246:253], 0, v208, v208 op_sel_hi:[0,0,0]
	v_cvt_pk_bf16_f32 v16, v96, v97
	v_cvt_pk_bf16_f32 v17, v98, v99
	ds_write_b64 v201, v[16:17] offset:37888
	v_cvt_pk_bf16_f32 v18, v100, v101
	v_cvt_pk_bf16_f32 v19, v102, v103
	ds_write_b64 v201, v[18:19] offset:42624
	v_cvt_pk_bf16_f32 v20, v104, v105
	v_cvt_pk_bf16_f32 v21, v106, v107
	ds_write_b64 v201, v[20:21] offset:47360
	v_cvt_pk_bf16_f32 v22, v108, v109
	v_cvt_pk_bf16_f32 v23, v110, v111
	ds_write_b64 v201, v[22:23] offset:52096
	ds_read_b128 v[246:249], v211 offset:128
	ds_read_b128 v[250:253], v211 offset:144
	s_waitcnt lgkmcnt(10)
	v_mfma_scale_f32_32x32x64_f8f6f4 v[230:245], v[40:47], v[24:31], v[230:245], v208, v208 op_sel_hi:[0,0,0]
	v_cvt_pk_bf16_f32 v16, v112, v113
	v_cvt_pk_bf16_f32 v17, v114, v115
	ds_write_b64 v201, v[16:17] offset:56832
	v_cvt_pk_bf16_f32 v18, v116, v117
	v_cvt_pk_bf16_f32 v19, v118, v119
	ds_write_b64 v201, v[18:19] offset:61568
	v_cvt_pk_bf16_f32 v20, v120, v121
	v_cvt_pk_bf16_f32 v21, v122, v123
	ds_write_b64 v204, v[20:21] offset:28416
	v_cvt_pk_bf16_f32 v22, v124, v125
	v_cvt_pk_bf16_f32 v23, v126, v127
	ds_write_b64 v204, v[22:23] offset:33152
	v_cvt_pk_bf16_f32 v16, v128, v129
	v_cvt_pk_bf16_f32 v17, v130, v131
	ds_write_b64 v213, v[16:17] offset:38400
	ds_read_b128 v[24:27], v211 offset:192
	ds_read_b128 v[28:31], v211 offset:208
	s_waitcnt lgkmcnt(7)
	v_mfma_scale_f32_32x32x64_f8f6f4 v[230:245], v[48:55], v[246:253], v[230:245], v208, v208 op_sel_hi:[0,0,0]
	v_readlane_b32 s0, v227, s41
	s_ashr_i32 s1, s0, 31
	s_lshl_b64 s[0:1], s[0:1], 7
	s_or_b32 s0, s0, 64
	s_lshl_b64 s[2:3], s[0:1], 10
	v_lshl_add_u64 v[16:17], v[182:183], 0, s[2:3]
	v_add_co_u32_e32 v18, vcc, 0x2000, v16
	s_lshl_b64 s[0:1], s[0:1], 7
	s_nop 0
	v_addc_co_u32_e32 v19, vcc, 0, v17, vcc
	global_load_dwordx4 v[96:99], v[16:17], off nt
	global_load_dwordx4 v[100:103], v[18:19], off nt
	v_add_co_u32_e32 v18, vcc, 0x4000, v16
	s_nop 1
	v_addc_co_u32_e32 v19, vcc, 0, v17, vcc
	v_add_co_u32_e32 v20, vcc, 0x6000, v16
	s_nop 1
	v_addc_co_u32_e32 v21, vcc, 0, v17, vcc
	global_load_dwordx4 v[104:107], v[18:19], off nt
	ds_read_b128 v[246:249], v211
	ds_read_b128 v[250:253], v211 offset:16
	s_waitcnt lgkmcnt(2)
	v_mfma_scale_f32_32x32x64_f8f6f4 v[230:245], v[56:63], v[24:31], v[230:245], v208, v208 op_sel_hi:[0,0,0]
	global_load_dwordx4 v[108:111], v[20:21], off nt
	v_add_co_u32_e32 v18, vcc, 0x8000, v16
	s_nop 1
	v_addc_co_u32_e32 v19, vcc, 0, v17, vcc
	v_add_co_u32_e32 v20, vcc, 0xa000, v16
	s_nop 1
	v_addc_co_u32_e32 v21, vcc, 0, v17, vcc
	global_load_dwordx4 v[112:115], v[18:19], off nt
	global_load_dwordx4 v[116:119], v[20:21], off nt
	v_add_co_u32_e32 v18, vcc, 0xc000, v16
	s_nop 1
	v_addc_co_u32_e32 v19, vcc, 0, v17, vcc
	v_add_co_u32_e32 v16, vcc, 0xe000, v16
	s_nop 1
	v_addc_co_u32_e32 v17, vcc, 0, v17, vcc
	global_load_dwordx4 v[120:123], v[18:19], off nt
	global_load_dwordx4 v[124:127], v[16:17], off nt
	v_lshl_add_u64 v[16:17], v[184:185], 0, s[0:1]
	global_load_dwordx4 v[128:131], v[16:17], off nt
	ds_read_b128 v[24:27], v211 offset:64
	ds_read_b128 v[28:31], v211 offset:80
	v_mul_f32_e32 v180, v231, v231
	v_fmac_f32_e32 v180, v230, v230
	v_fmac_f32_e32 v180, v232, v232
	v_fmac_f32_e32 v180, v233, v233
	v_fmac_f32_e32 v180, v234, v234
	v_fmac_f32_e32 v180, v235, v235
	v_fmac_f32_e32 v180, v236, v236
	v_fmac_f32_e32 v180, v237, v237
	v_fmac_f32_e32 v180, v238, v238
	v_fmac_f32_e32 v180, v239, v239
	v_fmac_f32_e32 v180, v240, v240
	v_fmac_f32_e32 v180, v241, v241
	v_fmac_f32_e32 v180, v242, v242
	v_fmac_f32_e32 v180, v243, v243
	v_fmac_f32_e32 v180, v244, v244
	v_fmac_f32_e32 v180, v245, v245
	s_waitcnt lgkmcnt(2)
	v_mfma_scale_f32_32x32x64_f8f6f4 v[230:245], v[64:71], v[246:253], 0, v208, v208 op_sel_hi:[0,0,0]
	ds_read_b128 v[246:249], v211 offset:128
	ds_read_b128 v[250:253], v211 offset:144
	s_waitcnt lgkmcnt(2)
	v_mfma_scale_f32_32x32x64_f8f6f4 v[230:245], v[72:79], v[24:31], v[230:245], v208, v208 op_sel_hi:[0,0,0]
	ds_read_b128 v[24:27], v211 offset:192
	ds_read_b128 v[28:31], v211 offset:208
	s_waitcnt lgkmcnt(2)
	v_mfma_scale_f32_32x32x64_f8f6f4 v[230:245], v[80:87], v[246:253], v[230:245], v208, v208 op_sel_hi:[0,0,0]
	ds_read_b128 v[246:249], v211 offset:8704
	ds_read_b128 v[250:253], v211 offset:8720
	s_waitcnt lgkmcnt(2)
	v_mfma_scale_f32_32x32x64_f8f6f4 v[230:245], v[88:95], v[24:31], v[230:245], v208, v208 op_sel_hi:[0,0,0]
	ds_read_b128 v[24:27], v211 offset:8768
	ds_read_b128 v[28:31], v211 offset:8784
	s_nop 15
	s_nop 1
	v_fmac_f32_e32 v180, v230, v230
	v_fmac_f32_e32 v180, v231, v231
	v_fmac_f32_e32 v180, v232, v232
	v_fmac_f32_e32 v180, v233, v233
	v_fmac_f32_e32 v180, v234, v234
	v_fmac_f32_e32 v180, v235, v235
	v_fmac_f32_e32 v180, v236, v236
	v_fmac_f32_e32 v180, v237, v237
	v_fmac_f32_e32 v180, v238, v238
	v_fmac_f32_e32 v180, v239, v239
	v_fmac_f32_e32 v180, v240, v240
	v_fmac_f32_e32 v180, v241, v241
	v_fmac_f32_e32 v180, v242, v242
	v_fmac_f32_e32 v180, v243, v243
	v_fmac_f32_e32 v180, v244, v244
	v_fmac_f32_e32 v180, v245, v245
	s_waitcnt lgkmcnt(2)
	v_mfma_scale_f32_32x32x64_f8f6f4 v[230:245], v[32:39], v[246:253], 0, v208, v208 op_sel_hi:[0,0,0]
	ds_read_b128 v[246:249], v211 offset:8832
	ds_read_b128 v[250:253], v211 offset:8848
	s_waitcnt lgkmcnt(2)
	v_mfma_scale_f32_32x32x64_f8f6f4 v[230:245], v[40:47], v[24:31], v[230:245], v208, v208 op_sel_hi:[0,0,0]
	ds_read_b128 v[24:27], v211 offset:8896
	ds_read_b128 v[28:31], v211 offset:8912
	s_waitcnt lgkmcnt(2)
	v_mfma_scale_f32_32x32x64_f8f6f4 v[230:245], v[48:55], v[246:253], v[230:245], v208, v208 op_sel_hi:[0,0,0]
	ds_read_b128 v[246:249], v211 offset:8704
	ds_read_b128 v[250:253], v211 offset:8720
	s_waitcnt lgkmcnt(2)
	v_mfma_scale_f32_32x32x64_f8f6f4 v[230:245], v[56:63], v[24:31], v[230:245], v208, v208 op_sel_hi:[0,0,0]
	ds_read_b128 v[24:27], v211 offset:8768
	ds_read_b128 v[28:31], v211 offset:8784
	s_nop 15
	s_nop 1
	v_mul_f32_e32 v229, v231, v231
	v_fmac_f32_e32 v229, v230, v230
	v_fmac_f32_e32 v229, v232, v232
	v_fmac_f32_e32 v229, v233, v233
	v_fmac_f32_e32 v229, v234, v234
	v_fmac_f32_e32 v229, v235, v235
	v_fmac_f32_e32 v229, v236, v236
	v_fmac_f32_e32 v229, v237, v237
	v_fmac_f32_e32 v229, v238, v238
	v_fmac_f32_e32 v229, v239, v239
	v_fmac_f32_e32 v229, v240, v240
	v_fmac_f32_e32 v229, v241, v241
	v_fmac_f32_e32 v229, v242, v242
	v_fmac_f32_e32 v229, v243, v243
	v_fmac_f32_e32 v229, v244, v244
	v_fmac_f32_e32 v229, v245, v245
	s_waitcnt lgkmcnt(2)
	v_mfma_scale_f32_32x32x64_f8f6f4 v[230:245], v[64:71], v[246:253], 0, v208, v208 op_sel_hi:[0,0,0]
	ds_read_b128 v[246:249], v211 offset:8832
	ds_read_b128 v[250:253], v211 offset:8848
	s_waitcnt lgkmcnt(2)
	v_mfma_scale_f32_32x32x64_f8f6f4 v[230:245], v[72:79], v[24:31], v[230:245], v208, v208 op_sel_hi:[0,0,0]
	ds_read_b128 v[24:27], v211 offset:8896
	ds_read_b128 v[28:31], v211 offset:8912
	s_waitcnt lgkmcnt(2)
	v_mfma_scale_f32_32x32x64_f8f6f4 v[230:245], v[80:87], v[246:253], v[230:245], v208, v208 op_sel_hi:[0,0,0]
	s_waitcnt lgkmcnt(0)
	v_mfma_scale_f32_32x32x64_f8f6f4 v[230:245], v[88:95], v[24:31], v[230:245], v208, v208 op_sel_hi:[0,0,0]
	s_waitcnt vmcnt(9)
	v_cvt_pk_fp8_f32 v16, v136, v137
	v_cvt_pk_fp8_f32 v17, v148, v149
	v_cvt_pk_fp8_f32 v18, v160, v161
	v_cvt_pk_fp8_f32 v19, v144, v145
	v_cvt_pk_fp8_f32 v20, v156, v157
	v_cvt_pk_fp8_f32 v21, v140, v141
	v_cvt_pk_fp8_f32 v22, v152, v153
	v_cvt_pk_fp8_f32 v23, v164, v165
	v_cvt_pk_fp8_f32 v16, v138, v139 op_sel:[0,0,1]
	v_cvt_pk_fp8_f32 v17, v150, v151 op_sel:[0,0,1]
	v_cvt_pk_fp8_f32 v18, v162, v163 op_sel:[0,0,1]
	v_cvt_pk_fp8_f32 v19, v146, v147 op_sel:[0,0,1]
	v_cvt_pk_fp8_f32 v20, v158, v159 op_sel:[0,0,1]
	v_cvt_pk_fp8_f32 v21, v142, v143 op_sel:[0,0,1]
	v_cvt_pk_fp8_f32 v22, v154, v155 op_sel:[0,0,1]
	v_cvt_pk_fp8_f32 v23, v166, v167 op_sel:[0,0,1]
	s_nop 1
	ds_write_b32 v228, v16
	ds_write_b32 v228, v17 offset:2176
	ds_write_b32 v228, v18 offset:4352
	ds_write_b32 v228, v19 offset:6528
	ds_write_b32 v228, v20 offset:8704
	ds_write_b32 v228, v21 offset:10880
	ds_write_b32 v228, v22 offset:13056
	ds_write_b32 v228, v23 offset:15232
	v_fmac_f32_e32 v229, v230, v230
	v_fmac_f32_e32 v229, v231, v231
	v_fmac_f32_e32 v229, v232, v232
	v_fmac_f32_e32 v229, v233, v233
	v_fmac_f32_e32 v229, v234, v234
	v_fmac_f32_e32 v229, v235, v235
	v_fmac_f32_e32 v229, v236, v236
	v_fmac_f32_e32 v229, v237, v237
	v_fmac_f32_e32 v229, v238, v238
	v_fmac_f32_e32 v229, v239, v239
	v_fmac_f32_e32 v229, v240, v240
	v_fmac_f32_e32 v229, v241, v241
	v_fmac_f32_e32 v229, v242, v242
	v_fmac_f32_e32 v229, v243, v243
	v_fmac_f32_e32 v229, v244, v244
	v_fmac_f32_e32 v229, v245, v245
.LBB0_1613:
	s_waitcnt lgkmcnt(0)
	s_barrier
	ds_read_b128 v[238:241], v214 offset:38400
	ds_read_b128 v[242:245], v214 offset:38416
	ds_read_b128 v[246:249], v214 offset:57344
	ds_read_b128 v[250:253], v214 offset:57360
	ds_read_b128 v[16:19], v219
	ds_read_b64_tr_b16 v[20:21], v220
	ds_read_b64_tr_b16 v[22:23], v220 offset:2368
	ds_read_b128 v[24:27], v221
	ds_read_b64_tr_b16 v[28:29], v222
	ds_read_b64_tr_b16 v[30:31], v222 offset:2368
	ds_read_b128 v[230:233], v223
	ds_read_b64_tr_b16 v[234:235], v224
	ds_read_b64_tr_b16 v[236:237], v224 offset:2368
	s_waitcnt lgkmcnt(6)
	v_mfma_f32_32x32x16_bf16 v[0:15], v[16:19], v[20:23], v[0:15]
	ds_read_b128 v[16:19], v225
	ds_read_b64_tr_b16 v[20:21], v226
	ds_read_b64_tr_b16 v[22:23], v226 offset:2368
	s_waitcnt lgkmcnt(6)
	v_mfma_f32_32x32x16_bf16 v[0:15], v[24:27], v[28:31], v[0:15]
	v_lshlrev_b32_e32 v24, 16, v238
	v_and_b32_e32 v238, 0xffff0000, v238
	v_mul_f32_e32 v28, v238, v238
	v_fmac_f32_e32 v28, v24, v24
	v_lshlrev_b32_e32 v25, 16, v239
	v_and_b32_e32 v239, 0xffff0000, v239
	v_fmac_f32_e32 v28, v25, v25
	v_fmac_f32_e32 v28, v239, v239
	v_lshlrev_b32_e32 v26, 16, v240
	v_and_b32_e32 v240, 0xffff0000, v240
	v_fmac_f32_e32 v28, v26, v26
	v_fmac_f32_e32 v28, v240, v240
	v_lshlrev_b32_e32 v27, 16, v241
	v_and_b32_e32 v241, 0xffff0000, v241
	v_fmac_f32_e32 v28, v27, v27
	v_fmac_f32_e32 v28, v241, v241
	v_lshlrev_b32_e32 v24, 16, v242
	v_and_b32_e32 v242, 0xffff0000, v242
	v_fmac_f32_e32 v28, v24, v24
	v_fmac_f32_e32 v28, v242, v242
	v_lshlrev_b32_e32 v25, 16, v243
	v_and_b32_e32 v243, 0xffff0000, v243
	v_fmac_f32_e32 v28, v25, v25
	v_fmac_f32_e32 v28, v243, v243
	v_lshlrev_b32_e32 v26, 16, v244
	v_and_b32_e32 v244, 0xffff0000, v244
	v_fmac_f32_e32 v28, v26, v26
	v_fmac_f32_e32 v28, v244, v244
	v_lshlrev_b32_e32 v27, 16, v245
	v_and_b32_e32 v245, 0xffff0000, v245
	v_fmac_f32_e32 v28, v27, v27
	v_fmac_f32_e32 v28, v245, v245
	s_waitcnt lgkmcnt(3)
	v_mfma_f32_32x32x16_bf16 v[0:15], v[230:233], v[234:237], v[0:15]
	v_lshlrev_b32_e32 v24, 16, v246
	v_and_b32_e32 v246, 0xffff0000, v246
	v_mul_f32_e32 v29, v246, v246
	v_fmac_f32_e32 v29, v24, v24
	v_lshlrev_b32_e32 v25, 16, v247
	v_and_b32_e32 v247, 0xffff0000, v247
	v_fmac_f32_e32 v29, v25, v25
	v_fmac_f32_e32 v29, v247, v247
	v_lshlrev_b32_e32 v26, 16, v248
	v_and_b32_e32 v248, 0xffff0000, v248
	v_fmac_f32_e32 v29, v26, v26
	v_fmac_f32_e32 v29, v248, v248
	v_lshlrev_b32_e32 v27, 16, v249
	v_and_b32_e32 v249, 0xffff0000, v249
	v_fmac_f32_e32 v29, v27, v27
	v_fmac_f32_e32 v29, v249, v249
	v_lshlrev_b32_e32 v24, 16, v250
	v_and_b32_e32 v250, 0xffff0000, v250
	v_fmac_f32_e32 v29, v24, v24
	v_fmac_f32_e32 v29, v250, v250
	v_lshlrev_b32_e32 v25, 16, v251
	v_and_b32_e32 v251, 0xffff0000, v251
	v_fmac_f32_e32 v29, v25, v25
	v_fmac_f32_e32 v29, v251, v251
	v_lshlrev_b32_e32 v26, 16, v252
	v_and_b32_e32 v252, 0xffff0000, v252
	v_fmac_f32_e32 v29, v26, v26
	v_fmac_f32_e32 v29, v252, v252
	v_lshlrev_b32_e32 v27, 16, v253
	v_and_b32_e32 v253, 0xffff0000, v253
	v_fmac_f32_e32 v29, v27, v27
	v_fmac_f32_e32 v29, v253, v253
	s_waitcnt lgkmcnt(0)
	v_mfma_f32_32x32x16_bf16 v[0:15], v[16:19], v[20:23], v[0:15]
	v_fmac_f32_e32 v28, 0x3b800000, v180
	v_fmac_f32_e32 v29, 0x3b800000, v229
	v_mov_b32_e32 v250, v28
	v_mov_b32_e32 v251, v29
	ds_bpermute_b32 v249, v199, v250
	ds_bpermute_b32 v248, v199, v251
.LBB0_1615:
	s_nop 0
	ds_read_b128 v[16:19], v215
	ds_read_b128 v[20:23], v216 offset:37888
	ds_read_b128 v[24:27], v215 offset:64
	ds_read_b128 v[28:31], v216 offset:37952
	ds_read_b128 v[230:233], v215 offset:512
	s_add_i32 s44, s42, 2
	s_waitcnt lgkmcnt(5)
	v_add_f32_e32 v246, v250, v249
	v_add_f32_e32 v247, v251, v248
	v_cndmask_b32_e64 v246, v247, v246, s[6:7]
	v_fmamk_f32 v246, v246, 0x3c2aaaab, v209
	v_mul_f32_e32 v249, 0x4f800000, v246
	v_cmp_gt_f32_e32 vcc, s37, v246
	s_waitcnt lgkmcnt(3)
	v_mfma_f32_16x16x32_bf16 v[16:19], v[16:19], v[20:23], 0
	ds_read_b128 v[20:23], v215 offset:128
	ds_read_b128 v[234:237], v216 offset:38016
	s_cmp_ge_u32 s44, s39
	s_cselect_b64 s[0:1], -1, 0
	s_nop 1
	v_cndmask_b32_e32 v246, v246, v249, vcc
	v_sqrt_f32_e32 v249, v246
	s_nop 0
	v_add_u32_e32 v250, -1, v249
	v_fma_f32 v252, -v250, v249, v246
	v_add_u32_e32 v251, 1, v249
	s_waitcnt lgkmcnt(3)
	v_mfma_f32_16x16x32_bf16 v[16:19], v[24:27], v[28:31], v[16:19]
	ds_read_b128 v[24:27], v215 offset:192
	ds_read_b128 v[28:31], v216 offset:38080
	v_cmp_ge_f32_e64 s[10:11], 0, v252
	s_nop 1
	v_cndmask_b32_e64 v250, v249, v250, s[10:11]
	v_fma_f32 v249, -v251, v249, v246
	v_cmp_lt_f32_e64 s[10:11], 0, v249
	s_nop 1
	v_cndmask_b32_e64 v249, v250, v251, s[10:11]
	s_waitcnt lgkmcnt(2)
	v_mfma_f32_16x16x32_bf16 v[16:19], v[20:23], v[234:237], v[16:19]
	ds_read_b128 v[20:23], v215 offset:256
	ds_read_b128 v[234:237], v216 offset:38144
	v_mul_f32_e32 v250, 0x37800000, v249
	v_cndmask_b32_e32 v249, v249, v250, vcc
	v_cmp_class_f32_e32 vcc, v246, v210
	s_nop 1
	v_cndmask_b32_e32 v246, v249, v246, vcc
	v_div_scale_f32 v249, s[10:11], v246, v246, 1.0
	v_rcp_f32_e32 v250, v249
	s_waitcnt lgkmcnt(2)
	v_mfma_f32_16x16x32_bf16 v[16:19], v[24:27], v[28:31], v[16:19]
	ds_read_b128 v[24:27], v215 offset:320
	ds_read_b128 v[28:31], v216 offset:38208
	s_nop 0
	v_fma_f32 v248, -v249, v250, 1.0
	v_fmac_f32_e32 v250, v248, v250
	v_div_scale_f32 v248, vcc, 1.0, v246, 1.0
	v_mul_f32_e32 v251, v248, v250
	v_fma_f32 v253, -v249, v251, v248
	v_fmac_f32_e32 v251, v253, v250
	s_waitcnt lgkmcnt(2)
	v_mfma_f32_16x16x32_bf16 v[16:19], v[20:23], v[234:237], v[16:19]
	ds_read_b128 v[20:23], v215 offset:384
	ds_read_b128 v[234:237], v216 offset:38272
	v_fma_f32 v248, -v249, v251, v248
	s_nop 0
	v_div_fmas_f32 v248, v248, v250, v251
	v_div_fixup_f32 v246, v248, v246, 1.0
	s_waitcnt lgkmcnt(2)
	v_mfma_f32_16x16x32_bf16 v[16:19], v[24:27], v[28:31], v[16:19]
	ds_read_b128 v[24:27], v215 offset:448
	ds_read_b128 v[28:31], v216 offset:38336
	ds_read_b128 v[238:241], v216 offset:38400
	ds_write_b32 v203, v246
	s_and_b64 vcc, exec, s[0:1]
	s_waitcnt lgkmcnt(0)
	s_barrier
	v_mfma_f32_16x16x32_bf16 v[16:19], v[20:23], v[234:237], v[16:19]
	ds_read_b32 v20, v217
	v_mfma_f32_16x16x32_bf16 v[16:19], v[24:27], v[28:31], v[16:19]
	v_mfma_f32_16x16x32_bf16 v[16:19], v[230:233], v[238:241], v[16:19]
	ds_read_b128 v[246:249], v207
	ds_read_b128 v[250:253], v207 offset:16
	ds_read_b128 v[24:27], v207 offset:64
	ds_read_b128 v[28:31], v207 offset:80
	s_waitcnt lgkmcnt(4)
	s_nop 6
	v_fma_f32 v16, v16, v20, -v177
	v_fma_f32 v17, v17, v20, -v177
	v_fma_f32 v18, v18, v20, -v177
	v_fma_f32 v19, v19, v20, -v177
	v_exp_f32_e32 v16, v16
	v_exp_f32_e32 v17, v17
	v_exp_f32_e32 v18, v18
	v_exp_f32_e32 v19, v19
	v_add_f32_e32 v188, v188, v192
	v_add_f32_e32 v189, v189, v193
	v_add_f32_e32 v186, v186, v190
	v_add_f32_e32 v187, v187, v191
	v_add_f32_e32 v188, v188, v16
	v_add_f32_e32 v189, v189, v17
	v_add_f32_e32 v186, v186, v18
	v_add_f32_e32 v187, v187, v19
	v_bfe_u32 v20, v16, 16, 1
	v_bfe_u32 v21, v17, 16, 1
	v_bfe_u32 v22, v18, 16, 1
	v_bfe_u32 v23, v19, 16, 1
	v_add3_u32 v20, v16, v20, s38
	v_add3_u32 v21, v17, v21, s38
	v_add3_u32 v22, v18, v22, s38
	v_add3_u32 v23, v19, v23, s38
	ds_write_b16_d16_hi v218, v20
	ds_write_b16_d16_hi v218, v21 offset:144
	ds_write_b16_d16_hi v218, v22 offset:288
	ds_write_b16_d16_hi v218, v23 offset:432
	s_cbranch_vccnz .LBB0_1618
	s_waitcnt lgkmcnt(6)
	v_mfma_scale_f32_32x32x64_f8f6f4 v[230:245], v[32:39], v[246:253], 0, v208, v208 op_sel_hi:[0,0,0]
	v_cvt_pk_bf16_f32 v16, v136, v137
	v_cvt_pk_bf16_f32 v17, v138, v139
	ds_write_b64 v201, v[16:17] offset:0
	v_cvt_pk_bf16_f32 v18, v148, v149
	v_cvt_pk_bf16_f32 v19, v150, v151
	ds_write_b64 v201, v[18:19] offset:4736
	v_cvt_pk_bf16_f32 v20, v160, v161
	v_cvt_pk_bf16_f32 v21, v162, v163
	ds_write_b64 v201, v[20:21] offset:9472
	v_cvt_pk_bf16_f32 v22, v144, v145
	v_cvt_pk_bf16_f32 v23, v146, v147
	ds_write_b64 v201, v[22:23] offset:14208
	ds_read_b128 v[246:249], v207 offset:128
	ds_read_b128 v[250:253], v207 offset:144
	s_waitcnt lgkmcnt(10)
	v_mfma_scale_f32_32x32x64_f8f6f4 v[230:245], v[40:47], v[24:31], v[230:245], v208, v208 op_sel_hi:[0,0,0]
	v_cvt_pk_bf16_f32 v16, v156, v157
	v_cvt_pk_bf16_f32 v17, v158, v159
	ds_write_b64 v201, v[16:17] offset:18944
	v_cvt_pk_bf16_f32 v18, v140, v141
	v_cvt_pk_bf16_f32 v19, v142, v143
	ds_write_b64 v201, v[18:19] offset:23680
	v_cvt_pk_bf16_f32 v20, v152, v153
	v_cvt_pk_bf16_f32 v21, v154, v155
	ds_write_b64 v201, v[20:21] offset:28416
	v_cvt_pk_bf16_f32 v22, v164, v165
	v_cvt_pk_bf16_f32 v23, v166, v167
	ds_write_b64 v201, v[22:23] offset:33152
	v_cvt_pk_bf16_f32 v16, v132, v133
	v_cvt_pk_bf16_f32 v17, v134, v135
	ds_write_b64 v213, v[16:17] offset:512
	ds_read_b128 v[24:27], v207 offset:192
	ds_read_b128 v[28:31], v207 offset:208
	s_waitcnt lgkmcnt(7)
	v_mfma_scale_f32_32x32x64_f8f6f4 v[230:245], v[48:55], v[246:253], v[230:245], v208, v208 op_sel_hi:[0,0,0]
	s_add_i32 s2, s41, 1
	v_readlane_b32 s2, v227, s2
	s_ashr_i32 s3, s2, 31
	s_lshl_b64 s[10:11], s[2:3], 17
	v_lshl_add_u64 v[16:17], v[182:183], 0, s[10:11]
	v_add_co_u32_e32 v18, vcc, 0x2000, v16
	s_lshl_b64 s[2:3], s[2:3], 14
	s_nop 0
	v_addc_co_u32_e32 v19, vcc, 0, v17, vcc
	global_load_dwordx4 v[136:139], v[16:17], off nt
	global_load_dwordx4 v[148:151], v[18:19], off nt
	v_add_co_u32_e32 v18, vcc, 0x4000, v16
	s_nop 1
	v_addc_co_u32_e32 v19, vcc, 0, v17, vcc
	v_add_co_u32_e32 v20, vcc, 0x6000, v16
	s_nop 1
	v_addc_co_u32_e32 v21, vcc, 0, v17, vcc
	global_load_dwordx4 v[160:163], v[18:19], off nt
	ds_read_b128 v[246:249], v207
	ds_read_b128 v[250:253], v207 offset:16
	s_waitcnt lgkmcnt(2)
	v_mfma_scale_f32_32x32x64_f8f6f4 v[230:245], v[56:63], v[24:31], v[230:245], v208, v208 op_sel_hi:[0,0,0]
	global_load_dwordx4 v[144:147], v[20:21], off nt
	v_add_co_u32_e32 v18, vcc, 0x8000, v16
	s_nop 1
	v_addc_co_u32_e32 v19, vcc, 0, v17, vcc
	v_add_co_u32_e32 v20, vcc, 0xa000, v16
	s_nop 1
	v_addc_co_u32_e32 v21, vcc, 0, v17, vcc
	global_load_dwordx4 v[156:159], v[18:19], off nt
	global_load_dwordx4 v[140:143], v[20:21], off nt
	v_add_co_u32_e32 v18, vcc, 0xc000, v16
	s_nop 1
	v_addc_co_u32_e32 v19, vcc, 0, v17, vcc
	v_add_co_u32_e32 v16, vcc, 0xe000, v16
	s_nop 1
	v_addc_co_u32_e32 v17, vcc, 0, v17, vcc
	global_load_dwordx4 v[152:155], v[18:19], off nt
	global_load_dwordx4 v[164:167], v[16:17], off nt
	v_lshl_add_u64 v[16:17], v[184:185], 0, s[2:3]
	global_load_dwordx4 v[132:135], v[16:17], off nt
	ds_read_b128 v[24:27], v207 offset:64
	ds_read_b128 v[28:31], v207 offset:80
	v_mul_f32_e32 v180, v231, v231
	v_fmac_f32_e32 v180, v230, v230
	v_fmac_f32_e32 v180, v232, v232
	v_fmac_f32_e32 v180, v233, v233
	v_fmac_f32_e32 v180, v234, v234
	v_fmac_f32_e32 v180, v235, v235
	v_fmac_f32_e32 v180, v236, v236
	v_fmac_f32_e32 v180, v237, v237
	v_fmac_f32_e32 v180, v238, v238
	v_fmac_f32_e32 v180, v239, v239
	v_fmac_f32_e32 v180, v240, v240
	v_fmac_f32_e32 v180, v241, v241
	v_fmac_f32_e32 v180, v242, v242
	v_fmac_f32_e32 v180, v243, v243
	v_fmac_f32_e32 v180, v244, v244
	v_fmac_f32_e32 v180, v245, v245
	s_waitcnt lgkmcnt(2)
	v_mfma_scale_f32_32x32x64_f8f6f4 v[230:245], v[64:71], v[246:253], 0, v208, v208 op_sel_hi:[0,0,0]
	ds_read_b128 v[246:249], v207 offset:128
	ds_read_b128 v[250:253], v207 offset:144
	s_waitcnt lgkmcnt(2)
	v_mfma_scale_f32_32x32x64_f8f6f4 v[230:245], v[72:79], v[24:31], v[230:245], v208, v208 op_sel_hi:[0,0,0]
	ds_read_b128 v[24:27], v207 offset:192
	ds_read_b128 v[28:31], v207 offset:208
	s_waitcnt lgkmcnt(2)
	v_mfma_scale_f32_32x32x64_f8f6f4 v[230:245], v[80:87], v[246:253], v[230:245], v208, v208 op_sel_hi:[0,0,0]
	ds_read_b128 v[246:249], v207 offset:8704
	ds_read_b128 v[250:253], v207 offset:8720
	s_waitcnt lgkmcnt(2)
	v_mfma_scale_f32_32x32x64_f8f6f4 v[230:245], v[88:95], v[24:31], v[230:245], v208, v208 op_sel_hi:[0,0,0]
	ds_read_b128 v[24:27], v207 offset:8768
	ds_read_b128 v[28:31], v207 offset:8784
	s_nop 15
	s_nop 1
	v_fmac_f32_e32 v180, v230, v230
	v_fmac_f32_e32 v180, v231, v231
	v_fmac_f32_e32 v180, v232, v232
	v_fmac_f32_e32 v180, v233, v233
	v_fmac_f32_e32 v180, v234, v234
	v_fmac_f32_e32 v180, v235, v235
	v_fmac_f32_e32 v180, v236, v236
	v_fmac_f32_e32 v180, v237, v237
	v_fmac_f32_e32 v180, v238, v238
	v_fmac_f32_e32 v180, v239, v239
	v_fmac_f32_e32 v180, v240, v240
	v_fmac_f32_e32 v180, v241, v241
	v_fmac_f32_e32 v180, v242, v242
	v_fmac_f32_e32 v180, v243, v243
	v_fmac_f32_e32 v180, v244, v244
	v_fmac_f32_e32 v180, v245, v245
	s_waitcnt lgkmcnt(2)
	v_mfma_scale_f32_32x32x64_f8f6f4 v[230:245], v[32:39], v[246:253], 0, v208, v208 op_sel_hi:[0,0,0]
	ds_read_b128 v[246:249], v207 offset:8832
	ds_read_b128 v[250:253], v207 offset:8848
	s_waitcnt lgkmcnt(2)
	v_mfma_scale_f32_32x32x64_f8f6f4 v[230:245], v[40:47], v[24:31], v[230:245], v208, v208 op_sel_hi:[0,0,0]
	ds_read_b128 v[24:27], v207 offset:8896
	ds_read_b128 v[28:31], v207 offset:8912
	s_waitcnt lgkmcnt(2)
	v_mfma_scale_f32_32x32x64_f8f6f4 v[230:245], v[48:55], v[246:253], v[230:245], v208, v208 op_sel_hi:[0,0,0]
	ds_read_b128 v[246:249], v207 offset:8704
	ds_read_b128 v[250:253], v207 offset:8720
	s_waitcnt lgkmcnt(2)
	v_mfma_scale_f32_32x32x64_f8f6f4 v[230:245], v[56:63], v[24:31], v[230:245], v208, v208 op_sel_hi:[0,0,0]
	ds_read_b128 v[24:27], v207 offset:8768
	ds_read_b128 v[28:31], v207 offset:8784
	s_nop 15
	s_nop 1
	v_mul_f32_e32 v229, v231, v231
	v_fmac_f32_e32 v229, v230, v230
	v_fmac_f32_e32 v229, v232, v232
	v_fmac_f32_e32 v229, v233, v233
	v_fmac_f32_e32 v229, v234, v234
	v_fmac_f32_e32 v229, v235, v235
	v_fmac_f32_e32 v229, v236, v236
	v_fmac_f32_e32 v229, v237, v237
	v_fmac_f32_e32 v229, v238, v238
	v_fmac_f32_e32 v229, v239, v239
	v_fmac_f32_e32 v229, v240, v240
	v_fmac_f32_e32 v229, v241, v241
	v_fmac_f32_e32 v229, v242, v242
	v_fmac_f32_e32 v229, v243, v243
	v_fmac_f32_e32 v229, v244, v244
	v_fmac_f32_e32 v229, v245, v245
	s_waitcnt lgkmcnt(2)
	v_mfma_scale_f32_32x32x64_f8f6f4 v[230:245], v[64:71], v[246:253], 0, v208, v208 op_sel_hi:[0,0,0]
	ds_read_b128 v[246:249], v207 offset:8832
	ds_read_b128 v[250:253], v207 offset:8848
	s_waitcnt lgkmcnt(2)
	v_mfma_scale_f32_32x32x64_f8f6f4 v[230:245], v[72:79], v[24:31], v[230:245], v208, v208 op_sel_hi:[0,0,0]
	ds_read_b128 v[24:27], v207 offset:8896
	ds_read_b128 v[28:31], v207 offset:8912
	s_waitcnt lgkmcnt(2)
	v_mfma_scale_f32_32x32x64_f8f6f4 v[230:245], v[80:87], v[246:253], v[230:245], v208, v208 op_sel_hi:[0,0,0]
	s_waitcnt lgkmcnt(0)
	v_mfma_scale_f32_32x32x64_f8f6f4 v[230:245], v[88:95], v[24:31], v[230:245], v208, v208 op_sel_hi:[0,0,0]
	s_waitcnt vmcnt(9)
	v_cvt_pk_fp8_f32 v16, v96, v97
	v_cvt_pk_fp8_f32 v17, v100, v101
	v_cvt_pk_fp8_f32 v18, v104, v105
	v_cvt_pk_fp8_f32 v19, v108, v109
	v_cvt_pk_fp8_f32 v20, v112, v113
	v_cvt_pk_fp8_f32 v21, v116, v117
	v_cvt_pk_fp8_f32 v22, v120, v121
	v_cvt_pk_fp8_f32 v23, v124, v125
	v_cvt_pk_fp8_f32 v16, v98, v99 op_sel:[0,0,1]
	v_cvt_pk_fp8_f32 v17, v102, v103 op_sel:[0,0,1]
	v_cvt_pk_fp8_f32 v18, v106, v107 op_sel:[0,0,1]
	v_cvt_pk_fp8_f32 v19, v110, v111 op_sel:[0,0,1]
	v_cvt_pk_fp8_f32 v20, v114, v115 op_sel:[0,0,1]
	v_cvt_pk_fp8_f32 v21, v118, v119 op_sel:[0,0,1]
	v_cvt_pk_fp8_f32 v22, v122, v123 op_sel:[0,0,1]
	v_cvt_pk_fp8_f32 v23, v126, v127 op_sel:[0,0,1]
	s_nop 1
	ds_write_b32 v228, v16 offset:17408
	ds_write_b32 v228, v17 offset:19584
	ds_write_b32 v228, v18 offset:21760
	ds_write_b32 v228, v19 offset:23936
	ds_write_b32 v228, v20 offset:26112
	ds_write_b32 v228, v21 offset:28288
	ds_write_b32 v228, v22 offset:30464
	ds_write_b32 v228, v23 offset:32640
	v_fmac_f32_e32 v229, v230, v230
	v_fmac_f32_e32 v229, v231, v231
	v_fmac_f32_e32 v229, v232, v232
	v_fmac_f32_e32 v229, v233, v233
	v_fmac_f32_e32 v229, v234, v234
	v_fmac_f32_e32 v229, v235, v235
	v_fmac_f32_e32 v229, v236, v236
	v_fmac_f32_e32 v229, v237, v237
	v_fmac_f32_e32 v229, v238, v238
	v_fmac_f32_e32 v229, v239, v239
	v_fmac_f32_e32 v229, v240, v240
	v_fmac_f32_e32 v229, v241, v241
	v_fmac_f32_e32 v229, v242, v242
	v_fmac_f32_e32 v229, v243, v243
	v_fmac_f32_e32 v229, v244, v244
	v_fmac_f32_e32 v229, v245, v245
.LBB0_1618:
	s_waitcnt lgkmcnt(0)
	s_barrier
	ds_read_b128 v[238:241], v214 offset:512
	ds_read_b128 v[242:245], v214 offset:528
	ds_read_b128 v[246:249], v214 offset:19456
	ds_read_b128 v[250:253], v214 offset:19472
	ds_read_b128 v[16:19], v219
	ds_read_b64_tr_b16 v[20:21], v220 offset:37888
	ds_read_b64_tr_b16 v[22:23], v220 offset:40256
	ds_read_b128 v[24:27], v221
	ds_read_b64_tr_b16 v[28:29], v222 offset:37888
	ds_read_b64_tr_b16 v[30:31], v222 offset:40256
	ds_read_b128 v[230:233], v223
	ds_read_b64_tr_b16 v[234:235], v224 offset:37888
	ds_read_b64_tr_b16 v[236:237], v224 offset:40256
	s_and_b32 s2, s43, 63
	s_cmp_eq_u32 s2, 63
	s_mov_b64 s[2:3], -1
	s_waitcnt lgkmcnt(6)
	v_mfma_f32_32x32x16_bf16 v[0:15], v[16:19], v[20:23], v[0:15]
	ds_read_b128 v[16:19], v225
	ds_read_b64_tr_b16 v[20:21], v226 offset:37888
	ds_read_b64_tr_b16 v[22:23], v226 offset:40256
	s_waitcnt lgkmcnt(6)
	v_mfma_f32_32x32x16_bf16 v[0:15], v[24:27], v[28:31], v[0:15]
	s_waitcnt lgkmcnt(3)
	v_mfma_f32_32x32x16_bf16 v[0:15], v[230:233], v[234:237], v[0:15]
	s_waitcnt lgkmcnt(0)
	v_mfma_f32_32x32x16_bf16 v[0:15], v[16:19], v[20:23], v[0:15]
	s_cbranch_scc0 .LBB0_1620
	s_andn2_b64 vcc, exec, s[2:3]
	s_cbranch_vccnz .LBB0_1601
	s_branch .LBB0_1621
